# v23 + Q-fragment load wait ladders removed in MLA / stick-breaking / memory attention prologues (Q and first K/V tile loads in flight together)
# baseline (speedup 1.0000x reference)
; DI int get_tid() { int t = threadIdx.x; asm volatile("" : "+v"(t)); return t; }
; template <int DK, int MODE> ...
;     ...
;   const int tid = get_tid(), lane = tid & 63, wave = __builtin_amdgcn_readfirstlane(tid >> 6), l32 = lane & 31, h = lane >> 5;
;   const int tq0 = qb * 128 + 32 * wave;
;   const int qpos = tq0 + l32;
;   bf16x8 qf[NKS];
;   {
;     const bf16_t* qp = Q + (size_t)qpos * DK + h * 8;
; #pragma unroll
;     for (int ks = 0; ks < NKS; ++ks) qf[ks] = *(const bf16x8*)(qp + ks * 16);
; #pragma unroll
;     for (int ks = 0; ks < NKS; ++ks) asm volatile("" : "+v"(qf[ks]));
;   }
;   float Fref = 0.f;
;   if (MODE == 1) Fref = F[qb * 128];
;   f32x16 o0, o1;
; #pragma unroll
;   for (int e = 0; e < 16; ++e) { o0[e] = 0.f; o1[e] = 0.f; }
;   float m = -1e30f, lsum = 0.f, R = 1.f;
;     ...
;   auto gload = [&](int jt) {
; #pragma unroll
;     for (int i = 0; i < NKL; ++i) {
;       const int id = tid + 256 * i, row = id / KCH, ch = id % KCH;
;       rk[i] = *(const u32x4*)(K + (size_t)(jt * 64 + row) * DK + ch * 8);
;     }
; #pragma unroll
;     for (int i = 0; i < 2; ++i) {
;       const int id = tid + 256 * i, row = id >> 3, ch = id & 7;
;       rv[i] = *(const u32x4*)(Vt + (size_t)row * Skv + jt * 64 + ch * 8);
;     }
;     if (MODE == 1) rf = F[jt * 64 + (tid & 63)];
;   };
;   auto swrite = [&](int buf) {
; #pragma unroll
;     for (int i = 0; i < NKL; ++i) {
;       const int id = tid + 256 * i, row = id / KCH, ch = id % KCH;
;       *(u32x4*)(sK + buf * 64 * LDK + row * LDK + ch * 8) = rk[i];
;     }
; #pragma unroll
;     for (int i = 0; i < 2; ++i) {
;       const int id = tid + 256 * i, row = id >> 3, ch = id & 7;
;       *(u32x4*)(sV + buf * 64 * 72 + row * 72 + ch * 8) = rv[i];
;     }
;     if (MODE == 1) { if (tid < 64) sF[buf * 64 + tid] = Fref - rf; }
;   };
.LBB0_522:
	s_and_b64 s[0:1], s[56:57], exec
	s_cselect_b32 s0, s63, s64
	s_and_b64 vcc, exec, s[48:49]
	s_mov_b64 s[4:5], -1
	s_cbranch_vccz .LBB0_541
	s_load_dwordx2 s[20:21], s[18:19], 0x110
	s_load_dwordx4 s[8:11], s[18:19], 0x100
	v_mov_b32_e32 v36, v188
	s_load_dwordx4 s[4:7], s[18:19], 0x90
	v_mov_b32_e32 v161, v1
	s_waitcnt lgkmcnt(0)
	s_add_u32 s12, s8, s52
	s_addc_u32 s13, s9, s53
	s_add_u32 s22, s10, s52
	s_addc_u32 s23, s11, s53
	s_add_u32 s8, s20, s50
	v_readfirstlane_b32 s1, v36
	s_addc_u32 s9, s21, s51
	s_ashr_i32 s1, s1, 1
	s_lshl_b32 s2, s0, 7
	s_andn2_b32 s1, s1, 31
	v_and_b32_e32 v37, 31, v36
	s_add_i32 s1, s1, s2
	v_bfe_u32 v38, v36, 5, 1
	v_or_b32_e32 v152, s1, v37
	s_waitcnt vmcnt(7)
	v_mov_b64_e32 v[2:3], s[12:13]
	v_mad_i64_i32 v[2:3], s[12:13], v152, s78, v[2:3]
	v_lshlrev_b32_e32 v0, 4, v38
	v_lshl_add_u64 v[2:3], v[2:3], 0, v[0:1]
	global_load_dwordx4 v[80:83], v[2:3], off
	global_load_dwordx4 v[128:131], v[2:3], off offset:32
	global_load_dwordx4 v[124:127], v[2:3], off offset:64
	global_load_dwordx4 v[120:123], v[2:3], off offset:96
	global_load_dwordx4 v[116:119], v[2:3], off offset:128
	global_load_dwordx4 v[112:115], v[2:3], off offset:160
	v_mul_hi_i32 v2, v36, s69
	v_lshrrev_b32_e32 v3, 31, v2
	v_ashrrev_i32_e32 v2, 1, v2
	s_waitcnt vmcnt(7)
	v_add_u32_e32 v28, 0x100, v36
	v_add_u32_e32 v39, v2, v3
	v_mul_hi_i32 v6, v28, s69
	v_mul_lo_u32 v2, v39, 12
	v_lshrrev_b32_e32 v7, 31, v6
	v_ashrrev_i32_e32 v6, 1, v6
	v_add_u32_e32 v12, 0x200, v36
	v_sub_u32_e32 v40, v36, v2
	v_add_u32_e32 v41, v6, v7
	v_mul_hi_i32 v13, v12, s69
	v_lshlrev_b32_e32 v154, 3, v40
	v_mul_lo_u32 v6, v41, 12
	v_lshrrev_b32_e32 v18, 31, v13
	v_ashrrev_i32_e32 v13, 1, v13
	v_mov_b64_e32 v[10:11], s[22:23]
	v_ashrrev_i32_e32 v155, 31, v154
	v_sub_u32_e32 v42, v28, v6
	v_add_u32_e32 v43, v13, v18
	v_mad_i64_i32 v[2:3], s[12:13], v39, s78, v[10:11]
	v_lshlrev_b64 v[14:15], 1, v[154:155]
	v_lshlrev_b32_e32 v156, 3, v42
	v_mul_lo_u32 v13, v43, 12
	v_lshl_add_u64 v[2:3], v[2:3], 0, v[14:15]
	v_ashrrev_i32_e32 v157, 31, v156
	v_sub_u32_e32 v44, v12, v13
	v_ashrrev_i32_e32 v22, 3, v36
	v_mad_i64_i32 v[6:7], s[12:13], v41, s78, v[10:11]
	v_lshlrev_b64 v[16:17], 1, v[156:157]
	v_lshlrev_b32_e32 v158, 3, v44
	v_ashrrev_i32_e32 v23, 31, v22
	v_lshl_add_u64 v[6:7], v[6:7], 0, v[16:17]
	v_ashrrev_i32_e32 v159, 31, v158
	v_lshlrev_b64 v[20:21], 14, v[22:23]
	v_lshlrev_b32_e32 v23, 3, v36
	s_waitcnt vmcnt(6)
	v_ashrrev_i32_e32 v32, 3, v28
	v_mad_i64_i32 v[10:11], s[12:13], v43, s78, v[10:11]
	v_lshlrev_b64 v[18:19], 1, v[158:159]
	v_and_b32_e32 v23, 56, v23
	v_ashrrev_i32_e32 v33, 31, v32
	v_lshl_add_u64 v[10:11], v[10:11], 0, v[18:19]
	v_lshl_add_u64 v[24:25], s[8:9], 0, v[20:21]
	v_lshlrev_b32_e32 v160, 1, v23
	v_lshlrev_b64 v[34:35], 14, v[32:33]
	v_lshl_add_u64 v[24:25], v[24:25], 0, v[160:161]
	v_lshl_add_u64 v[28:29], s[8:9], 0, v[34:35]
	v_lshl_add_u64 v[28:29], v[28:29], 0, v[160:161]
	v_mul_lo_u32 v159, v39, s70
	v_lshlrev_b32_e32 v23, 4, v40
	v_lshl_add_u32 v23, v159, 1, v23
	v_mul_lo_u32 v161, v41, s70
	s_or_b32 s8, s1, 31
	s_movk_i32 s9, 0xd0
	s_or_b32 s2, s2, 64
	v_mad_u32_u24 v175, v37, s9, v0
	s_add_u32 s9, s20, s44
	v_mul_lo_u32 v172, v43, s70
	v_lshlrev_b32_e32 v0, 6, v37
	s_addc_u32 s13, s21, s45
	v_mul_lo_u32 v173, v22, s33
	v_sub_u32_e32 v157, v175, v0
	global_load_dwordx4 v[2:5], v[2:3], off
	s_add_u32 s12, s9, 0x80
	global_load_dwordx4 v[6:9], v[6:7], off
	v_lshlrev_b32_e32 v0, 4, v36
	global_load_dwordx4 v[10:13], v[10:11], off
	v_mul_lo_u32 v174, v32, s33
	global_load_dwordx4 v[24:27], v[24:25], off
	s_addc_u32 s13, s13, 0
	global_load_dwordx4 v[28:31], v[28:29], off
	v_and_b32_e32 v0, 0x70, v0
	v_or_b32_e32 v34, v34, v0
	v_or_b32_e32 v20, v20, v0
	s_add_u32 s10, s10, 0x3000
	v_lshl_add_u64 v[162:163], s[12:13], 0, v[34:35]
	v_lshl_add_u64 v[164:165], s[12:13], 0, v[20:21]
	s_addc_u32 s11, s11, 0
	v_lshlrev_b32_e32 v149, 2, v38
	v_mov_b32_e32 v0, v1
	v_ashrrev_i32_e32 v153, 31, v152
	s_mov_b32 s9, 0
	v_mov_b32_e32 v155, 0xf149f2ca
	v_mov_b32_e32 v151, 0
	s_waitcnt vmcnt(4)
	ds_write_b128 v23, v[2:5]
	v_lshlrev_b32_e32 v2, 4, v42
	v_lshl_add_u32 v2, v161, 1, v2
	s_waitcnt vmcnt(3)
	ds_write_b128 v2, v[6:9]
	v_lshlrev_b32_e32 v2, 4, v44
	v_lshl_add_u32 v2, v172, 1, v2
	s_waitcnt vmcnt(2)
	ds_write_b128 v2, v[10:13]
	v_lshl_add_u32 v2, v173, 1, v160
	s_waitcnt vmcnt(1)
	ds_write_b128 v2, v[24:27] offset:26624
	v_lshl_add_u32 v2, v174, 1, v160
	s_waitcnt vmcnt(0)
	ds_write_b128 v2, v[28:31] offset:26624
	v_mad_i64_i32 v[2:3], s[12:13], v43, s78, v[18:19]
	v_lshl_add_u64 v[166:167], s[10:11], 0, v[2:3]
	v_mad_i64_i32 v[2:3], s[12:13], v41, s78, v[16:17]
	v_lshl_add_u64 v[168:169], s[10:11], 0, v[2:3]
	v_mad_i64_i32 v[2:3], s[12:13], v39, s78, v[14:15]
	v_mov_b32_e32 v14, v1
	v_mov_b32_e32 v15, v1
	v_lshl_add_u64 v[170:171], s[10:11], 0, v[2:3]
	v_mov_b32_e32 v2, v1
	v_mov_b32_e32 v3, v1
	v_mov_b32_e32 v4, v1
	v_mov_b32_e32 v5, v1
	v_mov_b32_e32 v6, v1
	v_mov_b32_e32 v7, v1
	v_mov_b32_e32 v8, v1
	v_mov_b32_e32 v9, v1
	v_mov_b32_e32 v10, v1
	v_mov_b32_e32 v11, v1
	v_mov_b32_e32 v12, v1
	v_mov_b32_e32 v13, v1
	v_mov_b64_e32 v[30:31], v[14:15]
	v_mov_b64_e32 v[46:47], v[14:15]
	s_mov_b32 s10, 0
	v_mov_b64_e32 v[28:29], v[12:13]
	v_mov_b64_e32 v[26:27], v[10:11]
	v_mov_b64_e32 v[24:25], v[8:9]
	v_mov_b64_e32 v[22:23], v[6:7]
	v_mov_b64_e32 v[20:21], v[4:5]
	v_mov_b64_e32 v[18:19], v[2:3]
	v_mov_b64_e32 v[16:17], v[0:1]
	v_mov_b64_e32 v[44:45], v[12:13]
	v_mov_b64_e32 v[42:43], v[10:11]
	v_mov_b64_e32 v[40:41], v[8:9]
	v_mov_b64_e32 v[38:39], v[6:7]
	v_mov_b64_e32 v[36:37], v[4:5]
	v_mov_b64_e32 v[34:35], v[2:3]
	v_mov_b64_e32 v[32:33], v[0:1]
	s_waitcnt lgkmcnt(0)
	s_barrier
	v_lshlrev_b32_e32 v217, 1, v159
	v_lshl_add_u32 v217, v154, 1, v217
	v_lshlrev_b32_e32 v218, 1, v161
	v_lshl_add_u32 v218, v156, 1, v218
	v_lshlrev_b32_e32 v219, 1, v172
	v_lshl_add_u32 v219, v158, 1, v219
	v_lshl_add_u32 v220, v173, 1, v160
	v_lshl_add_u32 v221, v174, 1, v160
	s_branch .LBB0_526

; DI int get_tid() { int t = threadIdx.x; asm volatile("" : "+v"(t)); return t; }
; template <int DK, int MODE> ...
;     ...
;   const int tid = get_tid(), lane = tid & 63, wave = __builtin_amdgcn_readfirstlane(tid >> 6), l32 = lane & 31, h = lane >> 5;
;   const int tq0 = qb * 128 + 32 * wave;
;   const int qpos = tq0 + l32;
;   bf16x8 qf[NKS];
;   {
;     const bf16_t* qp = Q + (size_t)qpos * DK + h * 8;
; #pragma unroll
;     for (int ks = 0; ks < NKS; ++ks) qf[ks] = *(const bf16x8*)(qp + ks * 16);
; #pragma unroll
;     for (int ks = 0; ks < NKS; ++ks) asm volatile("" : "+v"(qf[ks]));
;   }
;   float Fref = 0.f;
;   if (MODE == 1) Fref = F[qb * 128];
;   f32x16 o0, o1;
; #pragma unroll
;   for (int e = 0; e < 16; ++e) { o0[e] = 0.f; o1[e] = 0.f; }
;   float m = -1e30f, lsum = 0.f, R = 1.f;
;     ...
;   auto gload = [&](int jt) {
; #pragma unroll
;     for (int i = 0; i < NKL; ++i) {
;       const int id = tid + 256 * i, row = id / KCH, ch = id % KCH;
;       rk[i] = *(const u32x4*)(K + (size_t)(jt * 64 + row) * DK + ch * 8);
;     }
; #pragma unroll
;     for (int i = 0; i < 2; ++i) {
;       const int id = tid + 256 * i, row = id >> 3, ch = id & 7;
;       rv[i] = *(const u32x4*)(Vt + (size_t)row * Skv + jt * 64 + ch * 8);
;     }
;     if (MODE == 1) rf = F[jt * 64 + (tid & 63)];
;   };
;   auto swrite = [&](int buf) {
; #pragma unroll
;     for (int i = 0; i < NKL; ++i) {
;       const int id = tid + 256 * i, row = id / KCH, ch = id % KCH;
;       *(u32x4*)(sK + buf * 64 * LDK + row * LDK + ch * 8) = rk[i];
;     }
; #pragma unroll
;     for (int i = 0; i < 2; ++i) {
;       const int id = tid + 256 * i, row = id >> 3, ch = id & 7;
;       *(u32x4*)(sV + buf * 64 * 72 + row * 72 + ch * 8) = rv[i];
;     }
;     if (MODE == 1) { if (tid < 64) sF[buf * 64 + tid] = Fref - rf; }
;   };
.LBB0_574:
	s_lshr_b32 s28, s1, 6
	s_load_dwordx4 s[40:43], s[18:19], 0xe8
	s_lshl_b32 s2, s28, 19
	v_readlane_b32 s4, v214, 0
	s_add_i32 s30, s4, s2
	s_and_b32 s2, s0, 63
	s_lshl_b32 s12, s2, 8
	s_lshl_b32 s2, s2, 7
	s_add_i32 s28, s28, s66
	s_mov_b32 s10, s16
	s_lshl_b64 s[22:23], s[30:31], 1
	s_or_b32 s29, s2, 64
	s_and_b32 s16, s1, 63
	s_lshl_b32 s20, s28, 19
	s_lshl_b32 s6, s28, 20
	s_load_dwordx2 s[8:9], s[18:19], 0xf8
	s_waitcnt lgkmcnt(0)
	s_add_u32 s24, s40, s6
	s_addc_u32 s25, s41, 0
	s_add_u32 s4, s42, s6
	s_addc_u32 s5, s43, 0
	s_waitcnt vmcnt(1)
	v_mov_b32_e32 v28, v188
	s_add_u32 s6, s8, s6
	s_addc_u32 s7, s9, 0
	v_readfirstlane_b32 s13, v28
	s_ashr_i32 s13, s13, 6
	s_lshl_b32 s21, s16, 7
	s_lshl_b32 s79, s13, 5
	v_and_b32_e32 v29, 31, v28
	s_add_i32 s79, s79, s21
	v_or_b32_e32 v132, s79, v29
	v_ashrrev_i32_e32 v133, 31, v132
	s_waitcnt vmcnt(0)
	v_bfe_u32 v30, v28, 5, 1
	v_lshlrev_b64 v[2:3], 7, v[132:133]
	v_lshl_add_u64 v[2:3], s[24:25], 0, v[2:3]
	v_lshlrev_b32_e32 v0, 4, v30
	v_lshl_add_u64 v[2:3], v[2:3], 0, v[0:1]
	global_load_dwordx4 v[80:83], v[2:3], off
	global_load_dwordx4 v[84:87], v[2:3], off offset:32
	global_load_dwordx4 v[88:91], v[2:3], off offset:64
	global_load_dwordx4 v[92:95], v[2:3], off offset:96
	v_ashrrev_i32_e32 v2, 31, v28
	v_add_u32_e32 v3, 0x100, v28
	v_ashrrev_i32_e32 v16, 3, v28
	v_lshlrev_b32_e32 v4, 3, v28
	v_lshrrev_b32_e32 v2, 29, v2
	v_ashrrev_i32_e32 v5, 31, v3
	v_ashrrev_i32_e32 v17, 31, v16
	v_and_b32_e32 v4, 56, v4
	v_ashrrev_i32_e32 v18, 3, v3
	v_add_u32_e32 v2, v28, v2
	v_lshrrev_b32_e32 v5, 29, v5
	v_lshlrev_b64 v[20:21], 14, v[16:17]
	v_lshlrev_b32_e32 v134, 1, v4
	v_ashrrev_i32_e32 v19, 31, v18
	v_ashrrev_i32_e32 v17, 3, v2
	v_and_b32_e32 v2, -8, v2
	v_add_u32_e32 v4, v3, v5
	s_lshl_b32 s16, s16, 1
	v_lshlrev_b64 v[22:23], 14, v[18:19]
	v_sub_u32_e32 v19, v28, v2
	v_and_b32_e32 v2, -8, v4
	s_or_b32 s24, s16, 1
	v_ashrrev_i32_e32 v31, 3, v4
	v_sub_u32_e32 v32, v3, v2
	v_lshl_add_u64 v[2:3], s[6:7], 0, v[20:21]
	v_lshl_add_u64 v[4:5], s[6:7], 0, v[22:23]
	s_lshl_b32 s6, s24, 6
	v_add_u32_e32 v6, s6, v17
	v_lshlrev_b32_e32 v136, 3, v19
	v_add_u32_e32 v8, s6, v31
	v_ashrrev_i32_e32 v7, 31, v6
	v_ashrrev_i32_e32 v137, 31, v136
	v_lshlrev_b32_e32 v138, 3, v32
	v_ashrrev_i32_e32 v9, 31, v8
	v_lshlrev_b64 v[6:7], 7, v[6:7]
	v_lshlrev_b64 v[24:25], 1, v[136:137]
	v_ashrrev_i32_e32 v139, 31, v138
	s_lshl_b32 s30, s24, 7
	v_lshlrev_b64 v[8:9], 7, v[8:9]
	v_lshl_add_u64 v[6:7], s[4:5], 0, v[6:7]
	v_mov_b32_e32 v135, v1
	v_lshlrev_b64 v[26:27], 1, v[138:139]
	v_lshl_add_u64 v[2:3], v[2:3], 0, s[30:31]
	v_lshl_add_u64 v[4:5], v[4:5], 0, s[30:31]
	v_lshl_add_u64 v[8:9], s[4:5], 0, v[8:9]
	v_lshl_add_u64 v[6:7], v[6:7], 0, v[24:25]
	v_lshl_add_u64 v[2:3], v[2:3], 0, v[134:135]
	v_lshl_add_u64 v[4:5], v[4:5], 0, v[134:135]
	v_lshl_add_u64 v[8:9], v[8:9], 0, v[26:27]
	v_mul_lo_u32 v137, v16, s33
	v_mul_u32_u24_e32 v16, 0x48, v29
	v_mul_lo_u32 v139, v18, s33
	v_lshl_add_u32 v149, v16, 1, v0
	v_add_u32_e32 v16, s2, v17
	v_add_u32_e32 v18, s2, v31
	v_and_b32_e32 v33, 63, v28
	v_lshlrev_b32_e32 v28, 4, v28
	global_load_dwordx4 v[96:99], v[6:7], off
	global_load_dwordx4 v[100:103], v[8:9], off
	global_load_dwordx4 v[104:107], v[2:3], off
	global_load_dwordx4 v[108:111], v[4:5], off
	v_mul_lo_u32 v151, v17, s33
	v_lshlrev_b32_e32 v0, 4, v19
	v_ashrrev_i32_e32 v17, 31, v16
	v_ashrrev_i32_e32 v19, 31, v18
	v_and_b32_e32 v28, 0x70, v28
	v_mul_lo_u32 v199, v31, s33
	v_lshl_add_u32 v35, v151, 1, v0
	v_lshlrev_b32_e32 v0, 4, v32
	v_lshlrev_b64 v[16:17], 7, v[16:17]
	v_lshlrev_b64 v[18:19], 7, v[18:19]
	v_mov_b32_e32 v14, v1
	v_mov_b32_e32 v15, v1
	v_cmp_gt_u32_e64 s[38:39], 32, v33
	v_cmp_eq_u32_e64 s[40:41], 0, v33
	v_lshl_add_u32 v33, v137, 1, v134
	v_lshl_add_u32 v34, v139, 1, v134
	v_lshl_add_u32 v32, v199, 1, v0
	v_or3_b32 v22, v22, s12, v28
	v_or3_b32 v20, v20, s12, v28
	v_lshl_add_u64 v[16:17], v[16:17], 0, v[24:25]
	v_lshl_add_u64 v[18:19], v[18:19], 0, v[26:27]
	v_mov_b32_e32 v2, v1
	v_mov_b32_e32 v3, v1
	v_mov_b32_e32 v4, v1
	v_mov_b32_e32 v5, v1
	v_mov_b32_e32 v6, v1
	v_mov_b32_e32 v7, v1
	v_mov_b32_e32 v8, v1
	v_mov_b32_e32 v9, v1
	v_mov_b32_e32 v10, v1
	v_mov_b32_e32 v11, v1
	v_mov_b32_e32 v12, v1
	v_mov_b32_e32 v13, v1
	v_lshlrev_b32_e32 v135, 2, v30
	v_lshl_add_u64 v[140:141], s[8:9], 0, v[22:23]
	v_lshl_add_u64 v[142:143], s[8:9], 0, v[20:21]
	v_lshl_add_u64 v[152:153], s[42:43], 0, v[16:17]
	v_lshl_add_u64 v[154:155], s[42:43], 0, v[18:19]
	v_mov_b32_e32 v0, v1
	v_mov_b64_e32 v[30:31], v[14:15]
	s_mov_b32 s6, 0
	v_mov_b32_e32 v156, 1.0
	s_add_i32 s30, s16, 2
	s_lshl_b32 s2, s13, 2
	s_or_b32 s12, s79, 31
	v_mov_b64_e32 v[28:29], v[12:13]
	v_mov_b64_e32 v[26:27], v[10:11]
	v_mov_b64_e32 v[24:25], v[8:9]
	v_mov_b64_e32 v[22:23], v[6:7]
	v_mov_b64_e32 v[20:21], v[4:5]
	v_mov_b64_e32 v[18:19], v[2:3]
	v_mov_b64_e32 v[16:17], v[0:1]
	s_waitcnt vmcnt(3)
	ds_write_b128 v35, v[96:99]
	s_waitcnt vmcnt(2)
	ds_write_b128 v32, v[100:103]
	s_waitcnt vmcnt(1)
	ds_write_b128 v33, v[104:107] offset:18432
	s_waitcnt vmcnt(0)
	ds_write_b128 v34, v[108:111] offset:18432
	v_mov_b64_e32 v[46:47], v[14:15]
	v_mov_b64_e32 v[44:45], v[12:13]
	v_mov_b64_e32 v[42:43], v[10:11]
	v_mov_b64_e32 v[40:41], v[8:9]
	v_mov_b64_e32 v[38:39], v[6:7]
	v_mov_b64_e32 v[36:37], v[4:5]
	v_mov_b64_e32 v[34:35], v[2:3]
	v_mov_b64_e32 v[32:33], v[0:1]
	s_waitcnt lgkmcnt(0)
	s_barrier
	s_cmpk_eq_i32 s29, 0xffc0
	s_mov_b64 s[4:5], -1
	s_cbranch_scc1 .LBB0_586

; DI int get_tid() { int t = threadIdx.x; asm volatile("" : "+v"(t)); return t; }
; DI u32x2 pack4(float a, float b, float c, float d) { u32x2 r; r.x = pack2(a, b); r.y = pack2(c, d); return r; }
; template <int DK, int MODE> ...
;     ...
;   const int tid = get_tid(), lane = tid & 63, wave = __builtin_amdgcn_readfirstlane(tid >> 6), l32 = lane & 31, h = lane >> 5;
;   const int tq0 = qb * 128 + 32 * wave;
;   const int qpos = tq0 + l32;
;   bf16x8 qf[NKS];
;   {
;     const bf16_t* qp = Q + (size_t)qpos * DK + h * 8;
; #pragma unroll
;     for (int ks = 0; ks < NKS; ++ks) qf[ks] = *(const bf16x8*)(qp + ks * 16);
; #pragma unroll
;     for (int ks = 0; ks < NKS; ++ks) asm volatile("" : "+v"(qf[ks]));
;   }
;   float Fref = 0.f;
;   if (MODE == 1) Fref = F[qb * 128];
;   f32x16 o0, o1;
; #pragma unroll
;   for (int e = 0; e < 16; ++e) { o0[e] = 0.f; o1[e] = 0.f; }
;   float m = -1e30f, lsum = 0.f, R = 1.f;
;   u32x4 rk[NKL], rv[2];
;   float rf = 0.f;
;   auto gload = [&](int jt) {
; #pragma unroll
;     for (int i = 0; i < NKL; ++i) {
;       const int id = tid + 256 * i, row = id / KCH, ch = id % KCH;
;       rk[i] = *(const u32x4*)(K + (size_t)(jt * 64 + row) * DK + ch * 8);
;     }
; #pragma unroll
;     for (int i = 0; i < 2; ++i) {
;       const int id = tid + 256 * i, row = id >> 3, ch = id & 7;
;       rv[i] = *(const u32x4*)(Vt + (size_t)row * Skv + jt * 64 + ch * 8);
;     }
;     if (MODE == 1) rf = F[jt * 64 + (tid & 63)];
;   };
;     ...
;   const bf16_t* gp = gate + (size_t)qpos * 1024;
;   bf16_t* op = outp + (size_t)qpos * 1024;
; #pragma unroll
;   for (int dt = 0; dt < 2; ++dt)
; #pragma unroll
;     for (int g = 0; g < 4; ++g) {
;       const int dv = 32 * dt + 8 * g + 4 * h;
;       const u32x2 gv = *(const u32x2*)(gp + dv);
;       const f32x16& o = dt ? o1 : o0;
;       const float g0 = __uint_as_float(gv.x << 16), g1 = __uint_as_float(gv.x & 0xffff0000u), g2 = __uint_as_float(gv.y << 16), g3 = __uint_as_float(gv.y & 0xffff0000u);
;       *(u32x2*)(op + dv) = pack4(o[4 * g] * inv * g0, o[4 * g + 1] * inv * g1, o[4 * g + 2] * inv * g2, o[4 * g + 3] * inv * g3);
;     }
.LBB0_588:
	s_lshl_b32 s2, s28, 7
	s_and_b32 s2, s2, 0x180
	s_add_u32 s6, s11, s2
	v_readlane_b32 s4, v214, 5
	s_addc_u32 s7, s4, 0
	v_lshlrev_b64 v[2:3], 11, v[132:133]
	v_lshl_add_u64 v[4:5], s[6:7], 0, v[2:3]
	v_lshlrev_b32_e32 v0, 1, v135
	v_lshl_add_u64 v[4:5], v[4:5], 0, v[0:1]
	global_load_dwordx2 v[6:7], v[4:5], off offset:512
	v_readlane_b32 s4, v214, 6
	s_add_u32 s4, s4, s2
	v_readlane_b32 s2, v214, 7
	s_addc_u32 s5, s2, 0
	v_lshl_add_u64 v[2:3], s[4:5], 0, v[2:3]
	v_lshl_add_u64 v[2:3], v[2:3], 0, v[0:1]
	s_lshl_b32 s2, s28, 14
	v_readlane_b32 s8, v214, 8
	s_add_i32 s2, s2, s8
	s_lshl_b32 s16, s20, 1
	s_movk_i32 s54, 0x90
	s_waitcnt vmcnt(0)
	v_lshlrev_b32_e32 v8, 16, v6
	v_and_b32_e32 v9, 0xffff0000, v6
	v_lshlrev_b32_e32 v6, 16, v7
	v_and_b32_e32 v7, 0xffff0000, v7
	v_pk_mul_f32 v[8:9], v[32:33], v[8:9]
	v_pk_mul_f32 v[6:7], v[34:35], v[6:7]
	v_cvt_pk_bf16_f32 v8, v8, v9
	v_cvt_pk_bf16_f32 v9, v6, v7
	global_load_dwordx2 v[6:7], v[4:5], off offset:528
	s_nop 0
	global_store_dwordx2 v[2:3], v[8:9], off offset:512
	s_waitcnt vmcnt(1)
	v_lshlrev_b32_e32 v8, 16, v6
	v_and_b32_e32 v9, 0xffff0000, v6
	v_lshlrev_b32_e32 v6, 16, v7
	v_and_b32_e32 v7, 0xffff0000, v7
	v_pk_mul_f32 v[8:9], v[36:37], v[8:9]
	v_pk_mul_f32 v[6:7], v[38:39], v[6:7]
	v_cvt_pk_bf16_f32 v8, v8, v9
	v_cvt_pk_bf16_f32 v9, v6, v7
	global_load_dwordx2 v[6:7], v[4:5], off offset:544
	s_nop 0
	global_store_dwordx2 v[2:3], v[8:9], off offset:528
	s_waitcnt vmcnt(1)
	v_lshlrev_b32_e32 v8, 16, v6
	v_and_b32_e32 v9, 0xffff0000, v6
	v_lshlrev_b32_e32 v6, 16, v7
	v_and_b32_e32 v7, 0xffff0000, v7
	v_pk_mul_f32 v[8:9], v[40:41], v[8:9]
	v_pk_mul_f32 v[6:7], v[42:43], v[6:7]
	v_cvt_pk_bf16_f32 v8, v8, v9
	v_cvt_pk_bf16_f32 v9, v6, v7
	global_load_dwordx2 v[6:7], v[4:5], off offset:560
	s_nop 0
	global_store_dwordx2 v[2:3], v[8:9], off offset:544
	s_waitcnt vmcnt(1)
	v_lshlrev_b32_e32 v8, 16, v6
	v_and_b32_e32 v9, 0xffff0000, v6
	v_lshlrev_b32_e32 v6, 16, v7
	v_and_b32_e32 v7, 0xffff0000, v7
	v_pk_mul_f32 v[8:9], v[44:45], v[8:9]
	v_pk_mul_f32 v[6:7], v[46:47], v[6:7]
	v_cvt_pk_bf16_f32 v8, v8, v9
	v_cvt_pk_bf16_f32 v9, v6, v7
	global_load_dwordx2 v[6:7], v[4:5], off offset:576
	s_nop 0
	global_store_dwordx2 v[2:3], v[8:9], off offset:560
	s_waitcnt vmcnt(1)
	v_lshlrev_b32_e32 v8, 16, v6
	v_and_b32_e32 v9, 0xffff0000, v6
	v_lshlrev_b32_e32 v6, 16, v7
	v_and_b32_e32 v7, 0xffff0000, v7
	v_pk_mul_f32 v[8:9], v[16:17], v[8:9]
	v_pk_mul_f32 v[6:7], v[18:19], v[6:7]
	v_cvt_pk_bf16_f32 v8, v8, v9
	v_cvt_pk_bf16_f32 v9, v6, v7
	global_load_dwordx2 v[6:7], v[4:5], off offset:592
	s_nop 0
	global_store_dwordx2 v[2:3], v[8:9], off offset:576
	s_waitcnt vmcnt(1)
	v_lshlrev_b32_e32 v8, 16, v6
	v_and_b32_e32 v9, 0xffff0000, v6
	v_lshlrev_b32_e32 v6, 16, v7
	v_and_b32_e32 v7, 0xffff0000, v7
	v_pk_mul_f32 v[8:9], v[20:21], v[8:9]
	v_pk_mul_f32 v[6:7], v[22:23], v[6:7]
	v_cvt_pk_bf16_f32 v8, v8, v9
	v_cvt_pk_bf16_f32 v9, v6, v7
	global_load_dwordx2 v[6:7], v[4:5], off offset:608
	s_nop 0
	global_load_dwordx2 v[4:5], v[4:5], off offset:624
	s_nop 0
	global_store_dwordx2 v[2:3], v[8:9], off offset:592
	s_waitcnt vmcnt(2)
	v_lshlrev_b32_e32 v8, 16, v6
	v_and_b32_e32 v9, 0xffff0000, v6
	v_lshlrev_b32_e32 v6, 16, v7
	v_and_b32_e32 v7, 0xffff0000, v7
	v_pk_mul_f32 v[8:9], v[24:25], v[8:9]
	v_pk_mul_f32 v[6:7], v[26:27], v[6:7]
	v_cvt_pk_bf16_f32 v8, v8, v9
	v_cvt_pk_bf16_f32 v9, v6, v7
	s_waitcnt vmcnt(1)
	v_lshlrev_b32_e32 v6, 16, v4
	v_and_b32_e32 v7, 0xffff0000, v4
	v_lshlrev_b32_e32 v4, 16, v5
	v_and_b32_e32 v5, 0xffff0000, v5
	v_pk_mul_f32 v[6:7], v[28:29], v[6:7]
	v_pk_mul_f32 v[4:5], v[30:31], v[4:5]
	v_cvt_pk_bf16_f32 v6, v6, v7
	v_cvt_pk_bf16_f32 v7, v4, v5
	global_store_dwordx2 v[2:3], v[8:9], off offset:608
	global_store_dwordx2 v[2:3], v[6:7], off offset:624
	s_barrier
	s_load_dwordx4 s[40:43], s[18:19], 0x118
	s_load_dwordx2 s[12:13], s[18:19], 0x128
	v_mov_b32_e32 v28, v188
	s_waitcnt lgkmcnt(0)
	s_add_u32 s28, s40, s16
	s_addc_u32 s29, s41, 0
	s_lshl_b32 s2, s2, 1
	s_add_u32 s22, s42, s2
	s_addc_u32 s23, s43, 0
	s_add_u32 s24, s12, s2
	v_readfirstlane_b32 s2, v28
	s_addc_u32 s25, s13, 0
	s_ashr_i32 s2, s2, 1
	s_andn2_b32 s2, s2, 31
	v_and_b32_e32 v36, 31, v28
	s_add_i32 s2, s2, s21
	v_or_b32_e32 v130, s2, v36
	v_ashrrev_i32_e32 v131, 31, v130
	v_bfe_u32 v149, v28, 5, 1
	v_lshlrev_b64 v[2:3], 7, v[130:131]
	v_lshl_add_u64 v[2:3], s[28:29], 0, v[2:3]
	v_lshlrev_b32_e32 v0, 4, v149
	v_lshl_add_u64 v[2:3], v[2:3], 0, v[0:1]
	global_load_dwordx4 v[78:81], v[2:3], off
	global_load_dwordx4 v[74:77], v[2:3], off offset:32
	global_load_dwordx4 v[70:73], v[2:3], off offset:64
	global_load_dwordx4 v[66:69], v[2:3], off offset:96
	v_ashrrev_i32_e32 v2, 31, v28
	v_lshrrev_b32_e32 v2, 29, v2
	v_add_u32_e32 v2, v28, v2
	v_ashrrev_i32_e32 v18, 3, v2
	v_ashrrev_i32_e32 v19, 31, v18
	v_lshlrev_b64 v[10:11], 7, v[18:19]
	v_add_u32_e32 v19, 0x100, v28
	v_ashrrev_i32_e32 v6, 31, v19
	v_and_b32_e32 v2, -8, v2
	v_lshrrev_b32_e32 v6, 29, v6
	v_sub_u32_e32 v37, v28, v2
	v_add_u32_e32 v6, v19, v6
	v_lshlrev_b32_e32 v4, 3, v37
	v_ashrrev_i32_e32 v24, 3, v6
	v_and_b32_e32 v6, -8, v6
	v_ashrrev_i32_e32 v5, 31, v4
	v_sub_u32_e32 v38, v19, v6
	v_lshl_add_u64 v[2:3], s[22:23], 0, v[10:11]
	v_lshlrev_b64 v[14:15], 1, v[4:5]
	v_ashrrev_i32_e32 v25, 31, v24
	v_lshlrev_b32_e32 v8, 3, v38
	v_lshl_add_u64 v[2:3], v[2:3], 0, v[14:15]
	v_lshlrev_b64 v[12:13], 7, v[24:25]
	v_ashrrev_i32_e32 v9, 31, v8
	global_load_dwordx4 v[2:5], v[2:3], off
	v_lshl_add_u64 v[6:7], s[22:23], 0, v[12:13]
	v_lshlrev_b64 v[16:17], 1, v[8:9]
	v_lshl_add_u64 v[6:7], v[6:7], 0, v[16:17]
	global_load_dwordx4 v[6:9], v[6:7], off
	v_ashrrev_i32_e32 v20, 3, v28
	v_ashrrev_i32_e32 v34, 3, v19
	v_ashrrev_i32_e32 v21, 31, v20
	v_ashrrev_i32_e32 v35, 31, v34
	v_lshlrev_b64 v[22:23], 9, v[20:21]
	v_lshlrev_b32_e32 v21, 4, v28
	v_lshlrev_b64 v[30:31], 9, v[34:35]
	v_lshl_add_u64 v[26:27], s[24:25], 0, v[22:23]
	v_and_b32_e32 v22, 0x70, v21
	v_mov_b32_e32 v23, v1
	v_lshl_add_u64 v[30:31], s[24:25], 0, v[30:31]
	v_lshl_add_u64 v[136:137], v[26:27], 0, v[22:23]
	v_lshl_add_u64 v[138:139], v[30:31], 0, v[22:23]
	global_load_dwordx4 v[26:29], v[136:137], off
	global_load_dwordx4 v[30:33], v[138:139], off
	v_mul_lo_u32 v18, v18, s54
	v_lshl_add_u32 v151, v37, 4, v18
	s_movk_i32 s2, 0x2000
	v_mad_u64_u32 v[132:133], s[12:13], v20, s54, v[22:23]
	v_mad_u64_u32 v[134:135], s[12:13], v34, s54, v[22:23]
	s_waitcnt vmcnt(3)
; #define MFMA(a, b, c) __builtin_amdgcn_mfma_f32_32x32x16_bf16((a), (b), (c), 0, 0, 0)
; template <int DK, int MODE> ...
;     ...
; #pragma unroll
;       for (int ks = 0; ks < NKS; ++ks) { kf0[ks] = *(const bf16x8*)(kb + ks * 16); kf1[ks] = *(const bf16x8*)(kb + 32 * LDK + ks * 16); }
;       if (MODE == 1) {
;         const float* fb = sF + cur * 64 + 4 * h;
; #pragma unroll
;         for (int g = 0; g < 4; ++g) {
;           const f32x4 f0 = *(const f32x4*)(fb + 8 * g), f1 = *(const f32x4*)(fb + 32 + 8 * g);
;           s0[4 * g] = f0.x; s0[4 * g + 1] = f0.y; s0[4 * g + 2] = f0.z; s0[4 * g + 3] = f0.w;
;           s1[4 * g] = f1.x; s1[4 * g + 1] = f1.y; s1[4 * g + 2] = f1.z; s1[4 * g + 3] = f1.w;
;         }
;       } else {
; #pragma unroll
;         for (int e = 0; e < 16; ++e) { s0[e] = 0.f; s1[e] = 0.f; }
;       }
;       __builtin_amdgcn_iglp_opt(0);
;       __builtin_amdgcn_s_setprio(1);
; #pragma unroll
;       for (int ks = 0; ks < NKS; ++ks) { s0 = MFMA(kf0[ks], qf[ks], s0); s1 = MFMA(kf1[ks], qf[ks], s1); }
;       __builtin_amdgcn_s_setprio(0);
;       const bf16_t* vb = sV + cur * 64 * 72 + l32 * 72 + h * 8;
;       bf16x8 vf0[4], vf1[4];
; #pragma unroll
;       for (int j = 0; j < 4; ++j) { vf0[j] = *(const bf16x8*)(vb + j * 16); vf1[j] = *(const bf16x8*)(vb + 32 * 72 + j * 16); }
;       __builtin_amdgcn_sched_barrier(0);
;       const bool need_mask = CAUSAL && (key0 + 63 >= tq0);
;       bf16x8 pf[4];
;       if (MODE != 2) {
;         if (need_mask) {
; #pragma unroll
;           for (int e = 0; e < 16; ++e) {
;             const int key = key0 + 8 * (e >> 2) + 4 * h + (e & 3);
;             if (key > qpos) s0[e] = -1e30f;
;             if (key + 32 > qpos) s1[e] = -1e30f;
;           }
;         }
;         float mx = s0[0];
; #pragma unroll
;         for (int e = 1; e < 16; ++e) mx = fmaxf(mx, s0[e]);
; #pragma unroll
;         for (int e = 0; e < 16; ++e) mx = fmaxf(mx, s1[e]);
;         mx = fmaxf(mx, __shfl_xor(mx, 32));
;         if (__any(mx > m + 8.f)) {
;           const float mnew = fmaxf(m, mx);
;           const float alpha = __builtin_amdgcn_exp2f(m - mnew);
;           m = mnew; lsum *= alpha;
; #pragma unroll
;           for (int e = 0; e < 16; ++e) { o0[e] *= alpha; o1[e] *= alpha; }
;         }
;         float ps0 = 0.f, ps1 = 0.f, ps2 = 0.f, ps3 = 0.f;
; #pragma unroll
;         for (int e = 0; e < 16; e += 4) {
	ds_write_b128 v151, v[2:5]
	v_mul_lo_u32 v2, v24, s54
	v_lshl_add_u32 v152, v38, 4, v2
	v_lshl_add_u64 v[2:3], s[22:23], 0, v[14:15]
	s_waitcnt vmcnt(2)
	ds_write_b128 v152, v[6:9]
	v_mul_u32_u24_e32 v6, 0x48, v36
	v_and_b32_e32 v7, 64, v192
	v_lshl_add_u32 v0, v6, 1, v0
	v_xor_b32_e32 v6, 32, v192
	v_add_u32_e32 v7, 64, v7
	v_cmp_lt_i32_e32 vcc, v6, v7
	v_lshl_add_u64 v[140:141], v[2:3], 0, v[10:11]
	v_lshl_add_u64 v[4:5], s[22:23], 0, v[16:17]
	v_cndmask_b32_e32 v6, v192, v6, vcc
	v_add_co_u32_e32 v2, vcc, s2, v140
	v_lshl_add_u64 v[142:143], v[4:5], 0, v[12:13]
	s_nop 0
	v_addc_co_u32_e32 v3, vcc, 0, v141, vcc
	s_waitcnt vmcnt(1)
	ds_write_b128 v132, v[26:29] offset:18432
	s_waitcnt vmcnt(0)
	ds_write_b128 v134, v[30:33] offset:18432
	s_waitcnt lgkmcnt(0)
	s_barrier
	global_load_dwordx4 v[50:53], v[2:3], off
	v_add_co_u32_e32 v2, vcc, s2, v142
	global_load_dwordx4 v[58:61], v[136:137], off offset:128
	s_nop 0
	v_addc_co_u32_e32 v3, vcc, 0, v143, vcc
	global_load_dwordx4 v[54:57], v[2:3], off
	global_load_dwordx4 v[62:65], v[138:139], off offset:128
	ds_read_b128 v[2:5], v0 offset:4608
	ds_read_b128 v[18:21], v0
	ds_read_b128 v[34:37], v0 offset:32
	ds_read_b128 v[22:25], v0 offset:4640
	ds_read_b128 v[38:41], v0 offset:64
	ds_read_b128 v[26:29], v0 offset:4672
	ds_read_b128 v[42:45], v0 offset:96
	ds_read_b128 v[30:33], v0 offset:4704
	v_lshlrev_b32_e32 v133, 2, v6
	s_setprio 1
	s_waitcnt lgkmcnt(7)
	v_mfma_f32_32x32x16_bf16 v[2:17], v[2:5], v[78:81], 0
	s_waitcnt lgkmcnt(4)
	v_mfma_f32_32x32x16_bf16 v[2:17], v[22:25], v[74:77], v[2:17]
	s_waitcnt lgkmcnt(2)
	v_mfma_f32_32x32x16_bf16 v[2:17], v[26:29], v[70:73], v[2:17]
	s_waitcnt lgkmcnt(0)
	v_mfma_f32_32x32x16_bf16 v[2:17], v[30:33], v[66:69], v[2:17]
	s_setprio 0
	v_mfma_f32_32x32x16_bf16 v[18:33], v[18:21], v[78:81], 0
	ds_read_b128 v[82:85], v0 offset:18432
	ds_read_b128 v[86:89], v0 offset:18464
	ds_read_b128 v[90:93], v0 offset:23040
	ds_read_b128 v[94:97], v0 offset:23072
	ds_read_b128 v[98:101], v0 offset:18496
	ds_read_b128 v[102:105], v0 offset:18528
	ds_read_b128 v[106:109], v0 offset:23104
	v_mfma_f32_32x32x16_bf16 v[18:33], v[34:37], v[74:77], v[18:33]
	ds_read_b128 v[110:113], v0 offset:23136
	v_mfma_f32_32x32x16_bf16 v[18:33], v[38:41], v[70:73], v[18:33]
	v_mfma_f32_32x32x16_bf16 v[18:33], v[42:45], v[66:69], v[18:33]
	s_nop 11
	v_max_f32_e32 v34, v19, v19
	v_max_f32_e32 v35, v18, v18
	v_max_f32_e32 v34, v35, v34
	v_max3_f32 v34, v34, v20, v21
	v_max3_f32 v34, v34, v22, v23
	v_max3_f32 v34, v34, v24, v25
	v_max3_f32 v34, v34, v26, v27
	v_max3_f32 v34, v34, v28, v29
	v_max3_f32 v34, v34, v30, v31
	v_max3_f32 v34, v34, v32, v33
	v_max3_f32 v34, v34, v2, v3
	v_max3_f32 v34, v34, v4, v5
	v_max3_f32 v34, v34, v6, v7
	v_max3_f32 v34, v34, v8, v9
	v_max3_f32 v34, v34, v10, v11
	v_max3_f32 v34, v34, v12, v13
	v_max3_f32 v34, v34, v14, v15
	v_max3_f32 v34, v34, v16, v17
	ds_bpermute_b32 v35, v133, v34
	s_mov_b32 s2, 0xf149f2ca
	s_waitcnt lgkmcnt(0)
	v_max_f32_e32 v35, v35, v35
	v_max_f32_e32 v34, v34, v35
	v_cmp_lt_f32_e32 vcc, s2, v34
	s_cmp_eq_u64 vcc, 0
	v_max_f32_e32 v114, 0xf149f2ca, v34
	s_cselect_b64 vcc, -1, 0
	v_cndmask_b32_e32 v135, v114, v198, vcc
	v_sub_f32_e32 v19, v19, v135
	v_sub_f32_e32 v35, 0xf149f2ca, v114
	v_sub_f32_e32 v18, v18, v135
	v_exp_f32_e32 v114, v19
	v_sub_f32_e32 v19, v20, v135
	v_sub_f32_e32 v20, v21, v135
	v_sub_f32_e32 v21, v23, v135
	v_exp_f32_e32 v18, v18
	v_exp_f32_e32 v19, v19
	v_exp_f32_e32 v115, v20
	v_sub_f32_e32 v20, v22, v135
	v_exp_f32_e32 v22, v21
	v_sub_f32_e32 v21, v24, v135
	v_sub_f32_e32 v23, v25, v135
	v_sub_f32_e32 v25, v27, v135
	v_exp_f32_e32 v20, v20
	v_exp_f32_e32 v21, v21
	v_exp_f32_e32 v23, v23
	v_sub_f32_e32 v24, v26, v135
	v_exp_f32_e32 v26, v25
	v_sub_f32_e32 v25, v28, v135
	v_sub_f32_e32 v27, v29, v135
	v_sub_f32_e32 v29, v31, v135
	v_exp_f32_e32 v24, v24
	v_exp_f32_e32 v25, v25
	v_exp_f32_e32 v27, v27
	v_sub_f32_e32 v28, v30, v135
	v_exp_f32_e32 v30, v29
	v_sub_f32_e32 v29, v32, v135
	v_sub_f32_e32 v31, v33, v135
	v_sub_f32_e32 v3, v3, v135
	v_exp_f32_e32 v28, v28
	v_exp_f32_e32 v29, v29
	v_exp_f32_e32 v31, v31
	v_sub_f32_e32 v2, v2, v135
	v_exp_f32_e32 v32, v3
	v_sub_f32_e32 v3, v4, v135
	v_sub_f32_e32 v4, v5, v135
	v_sub_f32_e32 v5, v7, v135
	v_sub_f32_e32 v7, v9, v135
	v_sub_f32_e32 v9, v11, v135
	v_sub_f32_e32 v11, v13, v135
	v_sub_f32_e32 v13, v15, v135
	v_exp_f32_e32 v2, v2
	v_exp_f32_e32 v3, v3
	v_exp_f32_e32 v33, v4
	v_sub_f32_e32 v4, v6, v135
	v_exp_f32_e32 v6, v5
	v_sub_f32_e32 v5, v8, v135
	v_sub_f32_e32 v8, v10, v135
	v_exp_f32_e32 v10, v9
	v_sub_f32_e32 v9, v12, v135
	v_sub_f32_e32 v12, v14, v135
	v_exp_f32_e32 v14, v13
	v_sub_f32_e32 v13, v16, v135
	v_sub_f32_e32 v15, v17, v135
	v_pk_add_f32 v[16:17], v[18:19], 0 op_sel_hi:[1,0]
	v_pk_add_f32 v[116:117], v[114:115], 0 op_sel_hi:[1,0]
	v_exp_f32_e32 v4, v4
	v_exp_f32_e32 v5, v5
	v_exp_f32_e32 v7, v7
	v_pk_add_f32 v[16:17], v[20:21], v[16:17]
	v_pk_add_f32 v[116:117], v[22:23], v[116:117]
	v_exp_f32_e32 v8, v8
	v_exp_f32_e32 v9, v9
	v_exp_f32_e32 v11, v11
	v_pk_add_f32 v[16:17], v[24:25], v[16:17]
	v_pk_add_f32 v[116:117], v[26:27], v[116:117]
	v_exp_f32_e32 v35, v35
	v_exp_f32_e32 v12, v12
	v_exp_f32_e32 v13, v13
	v_exp_f32_e32 v15, v15
	v_pk_add_f32 v[16:17], v[28:29], v[16:17]
	v_pk_add_f32 v[154:155], v[30:31], v[116:117]
	v_cvt_pk_bf16_f32 v118, v2, v32
	v_cvt_pk_bf16_f32 v119, v3, v33
	v_pk_add_f32 v[2:3], v[2:3], v[16:17]
	v_pk_add_f32 v[16:17], v[32:33], v[154:155]
	v_cvt_pk_bf16_f32 v120, v4, v6
	v_cvt_pk_bf16_f32 v121, v5, v7
	v_pk_add_f32 v[2:3], v[4:5], v[2:3]
	v_pk_add_f32 v[4:5], v[6:7], v[16:17]
	v_pk_add_f32 v[2:3], v[8:9], v[2:3]
; #define MFMA(a, b, c) __builtin_amdgcn_mfma_f32_32x32x16_bf16((a), (b), (c), 0, 0, 0)
; DI unsigned pack2(float a, float b) { f32x2 v = {a, b}; return __builtin_bit_cast(unsigned, __builtin_convertvector(v, bf16v2)); }
; template <int DK, int MODE> ...
;     ...
;         if (__any(mx > m + 8.f)) {
;           const float mnew = fmaxf(m, mx);
;           const float alpha = __builtin_amdgcn_exp2f(m - mnew);
;           m = mnew; lsum *= alpha;
; #pragma unroll
;           for (int e = 0; e < 16; ++e) { o0[e] *= alpha; o1[e] *= alpha; }
;         }
;         float ps0 = 0.f, ps1 = 0.f, ps2 = 0.f, ps3 = 0.f;
; #pragma unroll
;         for (int e = 0; e < 16; e += 4) {
;           s0[e] = __builtin_amdgcn_exp2f(s0[e] - m); s0[e + 1] = __builtin_amdgcn_exp2f(s0[e + 1] - m); s0[e + 2] = __builtin_amdgcn_exp2f(s0[e + 2] - m); s0[e + 3] = __builtin_amdgcn_exp2f(s0[e + 3] - m);
;           ps0 += s0[e]; ps1 += s0[e + 1]; ps2 += s0[e + 2]; ps3 += s0[e + 3];
;         }
; #pragma unroll
;         for (int e = 0; e < 16; e += 4) {
;           s1[e] = __builtin_amdgcn_exp2f(s1[e] - m); s1[e + 1] = __builtin_amdgcn_exp2f(s1[e + 1] - m); s1[e + 2] = __builtin_amdgcn_exp2f(s1[e + 2] - m); s1[e + 3] = __builtin_amdgcn_exp2f(s1[e + 3] - m);
;           ps0 += s1[e]; ps1 += s1[e + 1]; ps2 += s1[e + 2]; ps3 += s1[e + 3];
;         }
;         lsum += (ps0 + ps1) + (ps2 + ps3);
;     ...
; #pragma unroll
;       for (int j = 0; j < 2; ++j) {
;         u32x4 a, b;
;         a.x = pack2(s0[8 * j], s0[8 * j + 1]); a.y = pack2(s0[8 * j + 2], s0[8 * j + 3]); a.z = pack2(s0[8 * j + 4], s0[8 * j + 5]); a.w = pack2(s0[8 * j + 6], s0[8 * j + 7]);
;         b.x = pack2(s1[8 * j], s1[8 * j + 1]); b.y = pack2(s1[8 * j + 2], s1[8 * j + 3]); b.z = pack2(s1[8 * j + 4], s1[8 * j + 5]); b.w = pack2(s1[8 * j + 6], s1[8 * j + 7]);
;         pf[j] = __builtin_bit_cast(bf16x8, a); pf[2 + j] = __builtin_bit_cast(bf16x8, b);
;       }
;       __builtin_amdgcn_s_setprio(1);
; #pragma unroll
;       for (int j = 0; j < 4; ++j) { o0 = MFMA(vf0[j], pf[j], o0); o1 = MFMA(vf1[j], pf[j], o1); }
;       __builtin_amdgcn_s_setprio(0);
;     }
;     __builtin_amdgcn_sched_barrier(0);
;     if (more) swrite(cur ^ 1);
;     if (MODE == 2) { const int done = __all(R == 0.f); if (lane == 0) sFlag[cur * 4 + wave] = done; }
;     __syncthreads();
	v_pk_add_f32 v[4:5], v[10:11], v[4:5]
	v_mul_f32_e32 v34, 0, v35
	v_pk_add_f32 v[2:3], v[12:13], v[2:3]
	v_pk_add_f32 v[4:5], v[14:15], v[4:5]
	v_cndmask_b32_e64 v34, v34, 0, vcc
	v_pk_add_f32 v[2:3], v[2:3], v[4:5]
	v_mov_b32_e32 v35, v34
	v_mov_b32_e32 v36, v34
	v_mov_b32_e32 v37, v34
	v_mov_b32_e32 v38, v34
	v_mov_b32_e32 v39, v34
	v_mov_b32_e32 v40, v34
	v_mov_b32_e32 v41, v34
	v_mov_b32_e32 v42, v34
	v_mov_b32_e32 v43, v34
	v_mov_b32_e32 v44, v34
	v_mov_b32_e32 v45, v34
	v_mov_b32_e32 v46, v34
	v_mov_b32_e32 v47, v34
	v_mov_b32_e32 v48, v34
	v_mov_b32_e32 v49, v34
	v_cvt_pk_bf16_f32 v114, v18, v114
	v_cvt_pk_bf16_f32 v115, v19, v115
	v_cvt_pk_bf16_f32 v116, v20, v22
	v_cvt_pk_bf16_f32 v117, v21, v23
	v_cvt_pk_bf16_f32 v122, v24, v26
	v_cvt_pk_bf16_f32 v123, v25, v27
	v_cvt_pk_bf16_f32 v124, v28, v30
	v_cvt_pk_bf16_f32 v125, v29, v31
	v_cvt_pk_bf16_f32 v126, v8, v10
	v_cvt_pk_bf16_f32 v127, v9, v11
	v_cvt_pk_bf16_f32 v128, v12, v14
	v_cvt_pk_bf16_f32 v129, v13, v15
	v_add_f32_e32 v153, v2, v3
	s_setprio 1
	v_mov_b64_e32 v[2:3], v[34:35]
	v_mov_b64_e32 v[4:5], v[36:37]
	v_mov_b64_e32 v[6:7], v[38:39]
	v_mov_b64_e32 v[8:9], v[40:41]
	v_mov_b64_e32 v[10:11], v[42:43]
	v_mov_b64_e32 v[12:13], v[44:45]
	v_mov_b64_e32 v[14:15], v[46:47]
	v_mov_b64_e32 v[16:17], v[48:49]
	v_mfma_f32_32x32x16_bf16 v[18:33], v[82:85], v[114:117], v[34:49]
	v_add_f32_e32 v154, v34, v153
	v_mfma_f32_32x32x16_bf16 v[2:17], v[90:93], v[114:117], v[2:17]
	v_mfma_f32_32x32x16_bf16 v[18:33], v[86:89], v[122:125], v[18:33]
	v_mfma_f32_32x32x16_bf16 v[2:17], v[94:97], v[122:125], v[2:17]
	v_mfma_f32_32x32x16_bf16 v[18:33], v[98:101], v[118:121], v[18:33]
	v_mfma_f32_32x32x16_bf16 v[2:17], v[106:109], v[118:121], v[2:17]
	v_mfma_f32_32x32x16_bf16 v[18:33], v[102:105], v[126:129], v[18:33]
	v_mfma_f32_32x32x16_bf16 v[2:17], v[110:113], v[126:129], v[2:17]
	s_setprio 0
	s_movk_i32 s2, 0x4000
	v_add_co_u32_e32 v34, vcc, s2, v140
	s_waitcnt vmcnt(3)
	ds_write_b128 v151, v[50:53] offset:9216
	v_addc_co_u32_e32 v35, vcc, 0, v141, vcc
	s_waitcnt vmcnt(1)
	ds_write_b128 v152, v[54:57] offset:9216
	ds_write_b128 v132, v[58:61] offset:27648
	s_waitcnt vmcnt(0)
	ds_write_b128 v134, v[62:65] offset:27648
	s_waitcnt lgkmcnt(0)
	s_barrier
	global_load_dwordx4 v[82:85], v[34:35], off
	v_add_co_u32_e32 v34, vcc, s2, v142
	global_load_dwordx4 v[90:93], v[136:137], off offset:256
	s_nop 0
	v_addc_co_u32_e32 v35, vcc, 0, v143, vcc
	global_load_dwordx4 v[86:89], v[34:35], off
	global_load_dwordx4 v[94:97], v[138:139], off offset:256
	ds_read_b128 v[34:37], v0 offset:13824
	ds_read_b128 v[50:53], v0 offset:9216
	ds_read_b128 v[98:101], v0 offset:9248
	ds_read_b128 v[54:57], v0 offset:13856
	ds_read_b128 v[102:105], v0 offset:9280
	ds_read_b128 v[58:61], v0 offset:13888
	ds_read_b128 v[62:65], v0 offset:13920
	ds_read_b128 v[156:159], v0 offset:9312
	s_setprio 1
	s_waitcnt lgkmcnt(7)
	v_mfma_f32_32x32x16_bf16 v[34:49], v[34:37], v[78:81], 0
	s_waitcnt lgkmcnt(4)
	v_mfma_f32_32x32x16_bf16 v[34:49], v[54:57], v[74:77], v[34:49]
	s_waitcnt lgkmcnt(2)
	v_mfma_f32_32x32x16_bf16 v[34:49], v[58:61], v[70:73], v[34:49]
	s_waitcnt lgkmcnt(1)
	v_mfma_f32_32x32x16_bf16 v[34:49], v[62:65], v[66:69], v[34:49]
	s_setprio 0
	v_mfma_f32_32x32x16_bf16 v[50:65], v[50:53], v[78:81], 0
	ds_read_b128 v[122:125], v0 offset:27648
	ds_read_b128 v[114:117], v0 offset:27680
	ds_read_b128 v[126:129], v0 offset:32256
	ds_read_b128 v[118:121], v0 offset:32288
	ds_read_b128 v[106:109], v0 offset:27712
	ds_read_b128 v[110:113], v0 offset:32320
	v_mfma_f32_32x32x16_bf16 v[50:65], v[98:101], v[74:77], v[50:65]
	ds_read_b128 v[98:101], v0 offset:32352
	v_mfma_f32_32x32x16_bf16 v[50:65], v[102:105], v[70:73], v[50:65]
	ds_read_b128 v[102:105], v0 offset:27744
	s_waitcnt lgkmcnt(8)
	v_mfma_f32_32x32x16_bf16 v[50:65], v[156:159], v[66:69], v[50:65]
	s_nop 11
	v_max_f32_e32 v153, v51, v51
	v_max_f32_e32 v155, v50, v50
	v_max_f32_e32 v153, v155, v153
	v_max3_f32 v153, v153, v52, v53
	v_max3_f32 v153, v153, v54, v55
	v_max3_f32 v153, v153, v56, v57
	v_max3_f32 v153, v153, v58, v59
	v_max3_f32 v153, v153, v60, v61
	v_max3_f32 v153, v153, v62, v63
	v_max3_f32 v153, v153, v64, v65
	v_max3_f32 v153, v153, v34, v35
	v_max3_f32 v153, v153, v36, v37
	v_max3_f32 v153, v153, v38, v39
	v_max3_f32 v153, v153, v40, v41
	v_max3_f32 v153, v153, v42, v43
	v_max3_f32 v153, v153, v44, v45
	v_max3_f32 v153, v153, v46, v47
	v_max3_f32 v153, v153, v48, v49
	ds_bpermute_b32 v155, v133, v153
	s_waitcnt lgkmcnt(0)
	v_max_f32_e32 v155, v155, v155
	v_max_f32_e32 v155, v153, v155
	v_add_f32_e32 v153, 0x41000000, v135
	v_cmp_gt_f32_e32 vcc, v155, v153
	s_cbranch_vccz .LBB0_590
	v_max_f32_e32 v153, v155, v155
	v_max_f32_e32 v155, v135, v135
	v_max_f32_e32 v155, v155, v153
	v_sub_f32_e32 v135, v135, v155
	v_exp_f32_e32 v156, v135
	v_add_f32_e32 v153, 0x41000000, v155
	v_mov_b32_e32 v135, v155
	v_pk_mul_f32 v[32:33], v[32:33], v[156:157] op_sel_hi:[1,0]
	v_pk_mul_f32 v[30:31], v[30:31], v[156:157] op_sel_hi:[1,0]
	v_pk_mul_f32 v[28:29], v[28:29], v[156:157] op_sel_hi:[1,0]
	v_pk_mul_f32 v[26:27], v[26:27], v[156:157] op_sel_hi:[1,0]
	v_pk_mul_f32 v[24:25], v[24:25], v[156:157] op_sel_hi:[1,0]
	v_pk_mul_f32 v[22:23], v[22:23], v[156:157] op_sel_hi:[1,0]
	v_pk_mul_f32 v[20:21], v[20:21], v[156:157] op_sel_hi:[1,0]
	v_pk_mul_f32 v[18:19], v[18:19], v[156:157] op_sel_hi:[1,0]
	v_pk_mul_f32 v[16:17], v[16:17], v[156:157] op_sel_hi:[1,0]
	v_pk_mul_f32 v[14:15], v[14:15], v[156:157] op_sel_hi:[1,0]
	v_pk_mul_f32 v[12:13], v[12:13], v[156:157] op_sel_hi:[1,0]
	v_pk_mul_f32 v[10:11], v[10:11], v[156:157] op_sel_hi:[1,0]
	v_pk_mul_f32 v[8:9], v[8:9], v[156:157] op_sel_hi:[1,0]
	v_pk_mul_f32 v[6:7], v[6:7], v[156:157] op_sel_hi:[1,0]
	v_pk_mul_f32 v[4:5], v[4:5], v[156:157] op_sel_hi:[1,0]
	v_pk_mul_f32 v[2:3], v[2:3], v[156:157] op_sel_hi:[1,0]
	v_mul_f32_e32 v154, v154, v156
